# v79 + flag-form intra-XCD level for the 4 later global barriers (cross-XCD level: memory-side counter + generation word)
# baseline (speedup 1.0000x reference)
.LBB0_233:
	s_mov_b64 s[6:7], s[0:1]
	s_getreg_b32 s8, hwreg(HW_REG_XCC_ID, 0, 4)
	s_waitcnt vmcnt(0)
	s_waitcnt vmcnt(0)
	v_add_u32_e32 v254, v254, v255
	v_cmp_ne_u32_e32 vcc, 17, v254
	s_nop 3
	s_cmp_eq_u64 vcc, 0
	s_cselect_b32 s99, 1, 0
	s_cmpk_lg_i32 s52, 0x100
	s_cselect_b32 s99, 0, s99
	s_barrier
	s_and_saveexec_b64 s[4:5], s[44:45]
	s_xor_b64 s[4:5], exec, s[4:5]
	s_cbranch_execz .LBB0_286
	s_cmp_eq_u32 s99, 0
	s_cbranch_scc1 .Lfb_skip_0
	s_load_dwordx2 s[8:9], s[0:1], 0x80
	s_and_b32 s10, s2, 7
	s_lshl_b32 s10, s10, 8
	s_add_i32 s10, s10, 0x1000
	s_lshr_b32 s11, s2, 3
	v_mov_b32_e32 v0, 1
	v_mov_b32_e32 v3, 0
	s_lshl_b32 s12, s11, 2
	v_mov_b32_e32 v1, s12
	s_mov_b32 s13, 0
	s_waitcnt lgkmcnt(0)
	s_add_u32 s18, s8, 0x3000
	s_addc_u32 s19, s9, 0
	s_add_u32 s8, s8, s10
	s_addc_u32 s9, s9, 0
	global_store_dword v1, v0, s[8:9]
	buffer_inv sc1
	s_cmp_eq_u32 s11, 0
	s_cbranch_scc1 .Lfb_lead_0

.LBB0_400:
	s_mov_b64 s[6:7], s[0:1]
	s_getreg_b32 s8, hwreg(HW_REG_XCC_ID, 0, 4)
	s_waitcnt vmcnt(0)
	s_barrier
	s_and_saveexec_b64 s[4:5], s[44:45]
	s_cbranch_execz .LBB0_452
	s_cmp_eq_u32 s99, 0
	s_cbranch_scc1 .Lfb_skip_1
	s_load_dwordx2 s[8:9], s[0:1], 0x80
	s_and_b32 s10, s2, 7
	s_lshl_b32 s10, s10, 8
	s_add_i32 s10, s10, 0x1000
	s_lshr_b32 s11, s2, 3
	v_mov_b32_e32 v0, 2
	v_mov_b32_e32 v3, 0
	s_lshl_b32 s12, s11, 2
	v_mov_b32_e32 v1, s12
	s_mov_b32 s13, 0
	s_waitcnt lgkmcnt(0)
	s_add_u32 s18, s8, 0x3000
	s_addc_u32 s19, s9, 0
	s_add_u32 s8, s8, s10
	s_addc_u32 s9, s9, 0
	global_store_dword v1, v0, s[8:9]
	buffer_inv sc1
	s_cmp_eq_u32 s11, 0
	s_cbranch_scc1 .Lfb_lead_1

.Lfb_lrel_1:
	s_mov_b64 exec, s[16:17]
	buffer_inv sc1
	buffer_wbl2 sc1
	s_waitcnt vmcnt(0)
	v_mov_b32_e32 v6, 1
	global_atomic_add v7, v3, v6, s[18:19] sc0
	s_waitcnt vmcnt(0)
	v_readfirstlane_b32 s12, v7
	s_add_i32 s12, s12, 1
	s_cmp_eq_u32 s12, 8
	s_cbranch_scc0 .Lfb_tpoll_1
	global_atomic_add v3, v6, s[18:19] offset:256
	s_branch .Lfb_trel_1
.Lfb_tpoll_1:
	v_mov_b32_e32 v8, 1
.Lfb_tloop_1:
	global_load_dword v7, v3, s[18:19] offset:256 sc1
	s_waitcnt vmcnt(0)
	v_cmp_ge_u32_e32 vcc, v7, v8
	s_and_b64 vcc, exec, vcc
	s_cbranch_vccnz .Lfb_trel_1
	s_sleep 1
	s_add_i32 s13, s13, 1
	s_cmp_lt_u32 s13, 0x1000
	s_cbranch_scc1 .Lfb_tloop_1
.Lfb_trel_1:
	global_store_dword v3, v0, s[8:9] offset:128

.Lfb_skip_1:
	s_add_i32 s9, 0, 0x23fe0
	v_mov_b32_e32 v0, s9
	s_load_dwordx2 s[6:7], s[6:7], 0x80
	s_waitcnt vmcnt(0) expcnt(0) lgkmcnt(0)
	ds_read_b32 v2, v0
	s_add_i32 s9, 0, 0x23fe4
	v_mov_b32_e32 v0, s9
	ds_read_b32 v0, v0
	s_and_b32 s33, s8, 15
	s_waitcnt lgkmcnt(1)
	v_cmp_ne_u32_e32 vcc, 0, v2
	s_cbranch_vccnz .LBB0_416
	s_load_dword s8, s[0:1], 0x90
	s_mov_b32 s55, 1
	v_mov_b32_e32 v16, 0
	s_waitcnt lgkmcnt(0)
	s_mul_i32 s54, s53, s8
	s_add_u32 s8, s6, 0x4200
	s_addc_u32 s9, s7, 0
	s_add_u32 s10, s6, 0x4400
	s_addc_u32 s11, s7, 0
	s_add_u32 s12, s6, 0x4500
	s_addc_u32 s13, s7, 0
	s_add_u32 s14, s6, 0x4600
	s_addc_u32 s15, s7, 0
	s_add_u32 s16, s6, 0x4700
	s_addc_u32 s17, s7, 0
	s_add_u32 s18, s6, 0x4800
	s_addc_u32 s19, s7, 0
	s_add_u32 s20, s6, 0x4900
	s_addc_u32 s21, s7, 0
	s_add_u32 s22, s6, 0x4a00
	s_addc_u32 s23, s7, 0
	s_add_u32 s24, s6, 0x4b00
	s_addc_u32 s25, s7, 0
	s_add_u32 s26, s6, 0x4c00
	s_addc_u32 s27, s7, 0
	s_add_u32 s28, s6, 0x4d00
	s_addc_u32 s29, s7, 0
	s_add_u32 s30, s6, 0x4e00
	s_addc_u32 s31, s7, 0
	s_add_u32 s34, s6, 0x4f00
	s_addc_u32 s35, s7, 0
	s_add_u32 s36, s6, 0x5000
	s_addc_u32 s37, s7, 0
	s_add_u32 s38, s6, 0x5100
	s_addc_u32 s39, s7, 0
	s_add_u32 s40, s6, 0x5200
	s_addc_u32 s41, s7, 0
	s_add_u32 s42, s6, 0x5300
	s_mul_i32 s54, s54, s52
	s_addc_u32 s43, s7, 0
	s_branch .LBB0_404

.LBB0_463:
	s_mov_b64 s[6:7], s[0:1]
	s_getreg_b32 s8, hwreg(HW_REG_XCC_ID, 0, 4)
	s_waitcnt vmcnt(0)
	s_barrier
	s_and_saveexec_b64 s[4:5], s[44:45]
	v_readlane_b32 s70, v250, 2
	v_readlane_b32 s71, v250, 3
	s_cbranch_execz .LBB0_515
	s_cmp_eq_u32 s99, 0
	s_cbranch_scc1 .Lfb_skip_2
	s_load_dwordx2 s[8:9], s[0:1], 0x80
	s_and_b32 s10, s2, 7
	s_lshl_b32 s10, s10, 8
	s_add_i32 s10, s10, 0x1000
	s_lshr_b32 s11, s2, 3
	v_mov_b32_e32 v0, 3
	v_mov_b32_e32 v3, 0
	s_lshl_b32 s12, s11, 2
	v_mov_b32_e32 v1, s12
	s_mov_b32 s13, 0
	s_waitcnt lgkmcnt(0)
	s_add_u32 s18, s8, 0x3000
	s_addc_u32 s19, s9, 0
	s_add_u32 s8, s8, s10
	s_addc_u32 s9, s9, 0
	global_store_dword v1, v0, s[8:9]
	buffer_inv sc1
	s_cmp_eq_u32 s11, 0
	s_cbranch_scc1 .Lfb_lead_2

.Lfb_lrel_2:
	s_mov_b64 exec, s[16:17]
	buffer_inv sc1
	buffer_wbl2 sc1
	s_waitcnt vmcnt(0)
	v_mov_b32_e32 v6, 1
	global_atomic_add v7, v3, v6, s[18:19] sc0
	s_waitcnt vmcnt(0)
	v_readfirstlane_b32 s12, v7
	s_add_i32 s12, s12, 1
	s_cmp_eq_u32 s12, 16
	s_cbranch_scc0 .Lfb_tpoll_2
	global_atomic_add v3, v6, s[18:19] offset:256
	s_branch .Lfb_trel_2
.Lfb_tpoll_2:
	v_mov_b32_e32 v8, 2

.LBB0_518:
	s_mov_b64 s[6:7], s[0:1]
	s_getreg_b32 s8, hwreg(HW_REG_XCC_ID, 0, 4)
	s_waitcnt vmcnt(0)
	s_barrier
	s_and_saveexec_b64 s[4:5], s[44:45]
	s_cbranch_execz .LBB0_570
	s_cmp_eq_u32 s99, 0
	s_cbranch_scc1 .Lfb_skip_3
	s_load_dwordx2 s[8:9], s[0:1], 0x80
	s_and_b32 s10, s2, 7
	s_lshl_b32 s10, s10, 8
	s_add_i32 s10, s10, 0x1000
	s_lshr_b32 s11, s2, 3
	v_mov_b32_e32 v0, 4
	v_mov_b32_e32 v3, 0
	s_lshl_b32 s12, s11, 2
	v_mov_b32_e32 v1, s12
	s_mov_b32 s13, 0
	s_waitcnt lgkmcnt(0)
	s_add_u32 s18, s8, 0x3000
	s_addc_u32 s19, s9, 0
	s_add_u32 s8, s8, s10
	s_addc_u32 s9, s9, 0
	global_store_dword v1, v0, s[8:9]
	buffer_inv sc1
	s_cmp_eq_u32 s11, 0
	s_cbranch_scc1 .Lfb_lead_3

.LBB0_612:
	s_mov_b64 s[8:9], s[0:1]
	s_waitcnt lgkmcnt(0)
	s_getreg_b32 s10, hwreg(HW_REG_XCC_ID, 0, 4)
	s_waitcnt vmcnt(0)
	s_barrier
	s_and_saveexec_b64 s[6:7], s[44:45]
	s_cbranch_execz .LBB0_664
	s_cmp_eq_u32 s99, 0
	s_cbranch_scc1 .Lfb_skip_4
	s_load_dwordx2 s[8:9], s[0:1], 0x80
	s_and_b32 s10, s2, 7
	s_lshl_b32 s10, s10, 8
	s_add_i32 s10, s10, 0x1000
	s_lshr_b32 s11, s2, 3
	v_mov_b32_e32 v0, 5
	v_mov_b32_e32 v3, 0
	s_lshl_b32 s12, s11, 2
	v_mov_b32_e32 v1, s12
	s_mov_b32 s13, 0
	s_waitcnt lgkmcnt(0)
	s_add_u32 s18, s8, 0x3000
	s_addc_u32 s19, s9, 0
	s_add_u32 s8, s8, s10
	s_addc_u32 s9, s9, 0
	global_store_dword v1, v0, s[8:9]
	buffer_inv sc1
	s_cmp_eq_u32 s11, 0
	s_cbranch_scc1 .Lfb_lead_4

.LBB0_1112:
	s_mov_b64 s[8:9], s[0:1]
	s_getreg_b32 s10, hwreg(HW_REG_XCC_ID, 0, 4)
	s_waitcnt vmcnt(0)
	s_barrier
	s_and_saveexec_b64 s[6:7], s[44:45]
	s_cbranch_execz .LBB0_1164
	s_cmp_eq_u32 s99, 0
	s_cbranch_scc1 .Lfb_skip_5
	s_load_dwordx2 s[8:9], s[0:1], 0x80
	s_and_b32 s10, s2, 7
	s_lshl_b32 s10, s10, 8
	s_add_i32 s10, s10, 0x1000
	s_lshr_b32 s11, s2, 3
	v_mov_b32_e32 v0, 6
	v_mov_b32_e32 v3, 0
	s_lshl_b32 s12, s11, 2
	v_mov_b32_e32 v1, s12
	s_mov_b32 s13, 0
	s_waitcnt lgkmcnt(0)
	s_add_u32 s18, s8, 0x3000
	s_addc_u32 s19, s9, 0
	s_add_u32 s8, s8, s10
	s_addc_u32 s9, s9, 0
	global_store_dword v1, v0, s[8:9]
	buffer_inv sc1
	s_cmp_eq_u32 s11, 0
	s_cbranch_scc1 .Lfb_lead_5

.LBB0_1210:
	s_mov_b64 s[8:9], s[0:1]
	s_getreg_b32 s10, hwreg(HW_REG_XCC_ID, 0, 4)
	s_waitcnt vmcnt(0)
	s_waitcnt lgkmcnt(0)
	s_barrier
	s_and_saveexec_b64 s[6:7], s[44:45]
	s_cbranch_execz .LBB0_1262
	s_cmp_eq_u32 s99, 0
	s_cbranch_scc1 .Lfb_skip_6
	s_load_dwordx2 s[8:9], s[0:1], 0x80
	s_and_b32 s10, s2, 7
	s_lshl_b32 s10, s10, 8
	s_add_i32 s10, s10, 0x1000
	s_lshr_b32 s11, s2, 3
	v_mov_b32_e32 v0, 7
	v_mov_b32_e32 v3, 0
	s_lshl_b32 s12, s11, 2
	v_mov_b32_e32 v1, s12
	s_mov_b32 s13, 0
	s_waitcnt lgkmcnt(0)
	s_add_u32 s18, s8, 0x3000
	s_addc_u32 s19, s9, 0
	s_add_u32 s8, s8, s10
	s_addc_u32 s9, s9, 0
	global_store_dword v1, v0, s[8:9]
	buffer_inv sc1
	s_cmp_eq_u32 s11, 0
	s_cbranch_scc1 .Lfb_lead_6

.LBB0_1278:
	s_mov_b64 s[8:9], s[0:1]
	s_getreg_b32 s10, hwreg(HW_REG_XCC_ID, 0, 4)
	s_waitcnt vmcnt(0)
	s_barrier
	s_and_saveexec_b64 s[6:7], s[44:45]
	s_cbranch_execz .LBB0_1330
	s_cmp_eq_u32 s99, 0
	s_cbranch_scc1 .Lfb_skip_7
	s_load_dwordx2 s[8:9], s[0:1], 0x80
	s_and_b32 s10, s2, 7
	s_lshl_b32 s10, s10, 8
	s_add_i32 s10, s10, 0x1000
	s_lshr_b32 s11, s2, 3
	v_mov_b32_e32 v0, 8
	v_mov_b32_e32 v3, 0
	s_lshl_b32 s12, s11, 2
	v_mov_b32_e32 v1, s12
	s_mov_b32 s13, 0
	s_waitcnt lgkmcnt(0)
	s_add_u32 s18, s8, 0x3000
	s_addc_u32 s19, s9, 0
	s_add_u32 s8, s8, s10
	s_addc_u32 s9, s9, 0
	global_store_dword v1, v0, s[8:9]
	buffer_inv sc1
	s_cmp_eq_u32 s11, 0
	s_cbranch_scc1 .Lfb_lead_7

.Lfb_lead_7:
	s_mov_b64 s[16:17], exec
	s_mov_b64 exec, 0xffffffff
	v_mbcnt_lo_u32_b32 v4, -1, 0
	v_lshlrev_b32_e32 v4, 2, v4
	v_mov_b32_e32 v0, 8

.Lfb_lrel_7:
	s_mov_b64 exec, s[16:17]
	buffer_inv sc1
	buffer_wbl2 sc1
	s_waitcnt vmcnt(0)
	v_mov_b32_e32 v6, 1
	global_atomic_add v7, v3, v6, s[18:19] sc0
	s_waitcnt vmcnt(0)
	v_readfirstlane_b32 s12, v7
	s_add_i32 s12, s12, 1
	s_cmp_eq_u32 s12, 24
	s_cbranch_scc0 .Lfb_tpoll_7
	global_atomic_add v3, v6, s[18:19] offset:256
	s_branch .Lfb_trel_7
.Lfb_tpoll_7:
	v_mov_b32_e32 v8, 3

.LBB0_1349:
	s_mov_b64 s[8:9], s[0:1]
	s_getreg_b32 s10, hwreg(HW_REG_XCC_ID, 0, 4)
	s_waitcnt vmcnt(0)
	s_barrier
	s_and_saveexec_b64 s[6:7], s[44:45]
	s_cbranch_execz .LBB0_1401
	s_cmp_eq_u32 s99, 0
	s_cbranch_scc1 .Lfb_skip_8
	s_load_dwordx2 s[8:9], s[0:1], 0x80
	s_and_b32 s10, s2, 7
	s_lshl_b32 s10, s10, 8
	s_add_i32 s10, s10, 0x1000
	s_lshr_b32 s11, s2, 3
	v_mov_b32_e32 v0, 9
	v_mov_b32_e32 v3, 0
	s_lshl_b32 s12, s11, 2
	v_mov_b32_e32 v1, s12
	s_mov_b32 s13, 0
	s_waitcnt lgkmcnt(0)
	s_add_u32 s18, s8, 0x3000
	s_addc_u32 s19, s9, 0
	s_add_u32 s8, s8, s10
	s_addc_u32 s9, s9, 0
	global_store_dword v1, v0, s[8:9]
	buffer_inv sc1
	s_cmp_eq_u32 s11, 0
	s_cbranch_scc1 .Lfb_lead_8

.Lfb_lead_8:
	s_mov_b64 s[16:17], exec
	s_mov_b64 exec, 0xffffffff
	v_mbcnt_lo_u32_b32 v4, -1, 0
	v_lshlrev_b32_e32 v4, 2, v4
	v_mov_b32_e32 v0, 9

.LBB0_1443:
	s_mov_b64 s[8:9], s[0:1]
	s_getreg_b32 s10, hwreg(HW_REG_XCC_ID, 0, 4)
	s_waitcnt vmcnt(0)
	s_waitcnt lgkmcnt(0)
	s_barrier
	s_and_saveexec_b64 s[6:7], s[44:45]
	s_cbranch_execz .LBB0_1495
	s_cmp_eq_u32 s99, 0
	s_cbranch_scc1 .Lfb_skip_9
	s_load_dwordx2 s[8:9], s[0:1], 0x80
	s_and_b32 s10, s2, 7
	s_lshl_b32 s10, s10, 8
	s_add_i32 s10, s10, 0x1000
	s_lshr_b32 s11, s2, 3
	v_mov_b32_e32 v0, 10
	v_mov_b32_e32 v3, 0
	s_lshl_b32 s12, s11, 2
	v_mov_b32_e32 v1, s12
	s_mov_b32 s13, 0
	s_waitcnt lgkmcnt(0)
	s_add_u32 s18, s8, 0x3000
	s_addc_u32 s19, s9, 0
	s_add_u32 s8, s8, s10
	s_addc_u32 s9, s9, 0
	global_store_dword v1, v0, s[8:9]
	buffer_inv sc1
	s_cmp_eq_u32 s11, 0
	s_cbranch_scc1 .Lfb_lead_9

.Lfb_lead_9:
	s_mov_b64 s[16:17], exec
	s_mov_b64 exec, 0xffffffff
	v_mbcnt_lo_u32_b32 v4, -1, 0
	v_lshlrev_b32_e32 v4, 2, v4
	v_mov_b32_e32 v0, 10

.LBB0_1935:
	s_mov_b64 s[8:9], s[0:1]
	s_getreg_b32 s10, hwreg(HW_REG_XCC_ID, 0, 4)
	s_waitcnt vmcnt(0)
	s_barrier
	s_and_saveexec_b64 s[6:7], s[44:45]
	s_cbranch_execz .LBB0_1987
	s_cmp_eq_u32 s99, 0
	s_cbranch_scc1 .Lfb_skip_10
	s_load_dwordx2 s[8:9], s[0:1], 0x80
	s_and_b32 s10, s2, 7
	s_lshl_b32 s10, s10, 8
	s_add_i32 s10, s10, 0x1000
	s_lshr_b32 s11, s2, 3
	v_mov_b32_e32 v0, 11
	v_mov_b32_e32 v3, 0
	s_lshl_b32 s12, s11, 2
	v_mov_b32_e32 v1, s12
	s_mov_b32 s13, 0
	s_waitcnt lgkmcnt(0)
	s_add_u32 s18, s8, 0x3000
	s_addc_u32 s19, s9, 0
	s_add_u32 s8, s8, s10
	s_addc_u32 s9, s9, 0
	global_store_dword v1, v0, s[8:9]
	buffer_inv sc1
	s_cmp_eq_u32 s11, 0
	s_cbranch_scc1 .Lfb_lead_10

.Lfb_lead_10:
	s_mov_b64 s[16:17], exec
	s_mov_b64 exec, 0xffffffff
	v_mbcnt_lo_u32_b32 v4, -1, 0
	v_lshlrev_b32_e32 v4, 2, v4
	v_mov_b32_e32 v0, 11

.Lfb_lrel_10:
	s_mov_b64 exec, s[16:17]
	buffer_inv sc1
	buffer_wbl2 sc1
	s_waitcnt vmcnt(0)
	v_mov_b32_e32 v6, 1
	global_atomic_add v7, v3, v6, s[18:19] sc0
	s_waitcnt vmcnt(0)
	v_readfirstlane_b32 s12, v7
	s_add_i32 s12, s12, 1
	s_cmp_eq_u32 s12, 32
	s_cbranch_scc0 .Lfb_tpoll_10
	global_atomic_add v3, v6, s[18:19] offset:256
	s_branch .Lfb_trel_10
.Lfb_tpoll_10:
	v_mov_b32_e32 v8, 4

.Lfb_skip_10:
	s_add_i32 s11, 0, 0x23fe0
	s_waitcnt vmcnt(17)
	v_mov_b32_e32 v0, s11
	s_load_dwordx2 s[8:9], s[8:9], 0x80
	s_waitcnt vmcnt(0) expcnt(0) lgkmcnt(0)
	ds_read_b32 v2, v0
	s_add_i32 s11, 0, 0x23fe4
	v_mov_b32_e32 v0, s11
	ds_read_b32 v0, v0
	s_and_b32 s33, s10, 15
	s_waitcnt lgkmcnt(1)
	v_cmp_ne_u32_e32 vcc, 0, v2
	s_cbranch_vccnz .LBB0_1951
	s_load_dword s10, s[0:1], 0x90
	s_mov_b32 s55, 1
	v_mov_b32_e32 v16, 0
	s_waitcnt lgkmcnt(0)
	s_mul_i32 s54, s53, s10
	s_add_u32 s10, s8, 0x4200
	s_addc_u32 s11, s9, 0
	s_add_u32 s12, s8, 0x4400
	s_addc_u32 s13, s9, 0
	s_add_u32 s14, s8, 0x4500
	s_addc_u32 s15, s9, 0
	s_add_u32 s16, s8, 0x4600
	s_addc_u32 s17, s9, 0
	s_add_u32 s18, s8, 0x4700
	s_addc_u32 s19, s9, 0
	s_add_u32 s20, s8, 0x4800
	s_addc_u32 s21, s9, 0
	s_add_u32 s22, s8, 0x4900
	s_addc_u32 s23, s9, 0
	s_add_u32 s24, s8, 0x4a00
	s_addc_u32 s25, s9, 0
	s_add_u32 s26, s8, 0x4b00
	s_addc_u32 s27, s9, 0
	s_add_u32 s28, s8, 0x4c00
	s_addc_u32 s29, s9, 0
	s_add_u32 s30, s8, 0x4d00
	s_addc_u32 s31, s9, 0
	s_add_u32 s34, s8, 0x4e00
	s_addc_u32 s35, s9, 0
	s_add_u32 s36, s8, 0x4f00
	s_addc_u32 s37, s9, 0
	s_add_u32 s38, s8, 0x5000
	s_addc_u32 s39, s9, 0
	s_add_u32 s40, s8, 0x5100
	s_addc_u32 s41, s9, 0
	s_add_u32 s42, s8, 0x5200
	s_addc_u32 s43, s9, 0
	s_add_u32 s48, s8, 0x5300
	s_mul_i32 s54, s54, s52
	s_addc_u32 s49, s9, 0
	s_branch .LBB0_1939
